# logits_job: xor-16/32 butterfly steps via v_permlane16/32_swap on copies instead of ds_bpermute (bit-identical sums)
# speedup vs baseline: 1.0129x; 1.0129x over previous
; __device__ __forceinline__ float bflo(unsigned w) { return __uint_as_float(w << 16); }
; __device__ __forceinline__ float bfhi(unsigned w) { return __uint_as_float(w & 0xffff0000u); }
; __device__ __forceinline__ float wave_sum(float v) {
; #pragma unroll
;     for (int o = 1; o < 64; o <<= 1) v += __shfl_xor(v, o);
;     return v;
; __device__ __forceinline__ void logits_job(const Args& a, const bf16* Z, int lane, int wave) {
;     ...
;         const v2u* xr = (const v2u*)(Z + (size_t)m * D) + lane;
;         f32x4 v[4]; float s = 0.f;
; #pragma unroll
;         for (int j = 0; j < 4; ++j) { const v2u w = xr[64 * j]; v[j] = (f32x4){bflo(w.x), bfhi(w.x), bflo(w.y), bfhi(w.y)}; s += (v[j][0] + v[j][1]) + (v[j][2] + v[j][3]); }
;         const float mean = wave_sum(s) * (1.f / D); float s2 = 0.f;
; #pragma unroll
;         for (int j = 0; j < 4; ++j) { v[j] = v[j] - mean; s2 += (v[j][0] * v[j][0] + v[j][1] * v[j][1]) + (v[j][2] * v[j][2] + v[j][3] * v[j][3]); }
;         const float rstd = 1.f / sqrtf(wave_sum(s2) * (1.f / D) + LN_EPS);
;         float mine = 0.f;
; #pragma unroll
;         for (int h = 0; h < 8; ++h) { float d = 0.f;
; #pragma unroll
;             for (int j = 0; j < 4; ++j) { const f32x4 w = ((const f32x4*)(WF + h * 1024))[64 * j + lane]; d += (v[j][0] * w[0] + v[j][1] * w[1]) + (v[j][2] * w[2] + v[j][3] * w[3]); }
;             d = wave_sum(d); if (lane == h) mine = d; }
.LBB0_417:
	s_ashr_i32 s7, s6, 31
	s_lshl_b64 s[12:13], s[6:7], 11
	v_lshl_add_u64 v[70:71], v[0:1], 0, s[12:13]
	s_waitcnt lgkmcnt(0)
	global_load_dwordx2 v[72:73], v[70:71], off
	global_load_dwordx2 v[74:75], v[70:71], off offset:512
	global_load_dwordx2 v[96:97], v[70:71], off offset:1024
	global_load_dwordx2 v[132:133], v[70:71], off offset:1536
	global_load_dwordx4 v[100:103], v[6:7], off
	global_load_dwordx4 v[104:107], v[8:9], off
	global_load_dwordx4 v[108:111], v[10:11], off
	global_load_dwordx4 v[112:115], v[12:13], off
	global_load_dwordx4 v[116:119], v[14:15], off
	global_load_dwordx4 v[120:123], v[16:17], off
	global_load_dwordx4 v[124:127], v[18:19], off
	global_load_dwordx4 v[128:131], v[20:21], off
	s_waitcnt vmcnt(0)
	v_lshlrev_b32_e32 v79, 16, v73
	v_lshlrev_b32_e32 v78, 16, v72
	v_and_b32_e32 v83, 0xffff0000, v73
	v_and_b32_e32 v82, 0xffff0000, v72
	v_lshlrev_b32_e32 v77, 16, v75
	v_lshlrev_b32_e32 v76, 16, v74
	v_and_b32_e32 v81, 0xffff0000, v75
	v_and_b32_e32 v80, 0xffff0000, v74
	v_lshlrev_b32_e32 v95, 16, v96
	v_and_b32_e32 v98, 0xffff0000, v96
	v_lshlrev_b32_e32 v73, 16, v132
	v_and_b32_e32 v96, 0xffff0000, v132
	v_lshlrev_b32_e32 v71, 16, v133
	v_and_b32_e32 v75, 0xffff0000, v133
	v_pk_add_f32 v[132:133], v[78:79], v[82:83]
	v_pk_add_f32 v[134:135], v[76:77], v[80:81]
	v_lshlrev_b32_e32 v94, 16, v97
	v_and_b32_e32 v97, 0xffff0000, v97
	v_add_f32_e32 v72, v132, v133
	v_pk_add_f32 v[132:133], v[134:135], v[134:135] op_sel:[0,1] op_sel_hi:[1,0]
	v_add_f32_e32 v70, v95, v98
	v_add_f32_e32 v74, v94, v97
	v_add_f32_e32 v72, 0, v72
	v_mov_b32_e32 v133, v96
	v_pk_add_f32 v[134:135], v[70:71], v[74:75]
	v_pk_add_f32 v[132:133], v[72:73], v[132:133]
	s_nop 0
	v_pk_add_f32 v[132:133], v[132:133], v[134:135]
	s_nop 0
	v_add_f32_e32 v70, v132, v133
	global_load_dwordx4 v[132:135], v[22:23], off
	global_load_dwordx4 v[136:139], v[24:25], off
	s_nop 1
	v_mov_b32_dpp v72, v70 quad_perm:[1,0,3,2] row_mask:0xf bank_mask:0xf
	global_load_dwordx4 v[140:143], v[26:27], off
	global_load_dwordx4 v[144:147], v[28:29], off
	global_load_dwordx4 v[148:151], v[30:31], off
	global_load_dwordx4 v[152:155], v[32:33], off
	global_load_dwordx4 v[156:159], v[34:35], off
	s_waitcnt lgkmcnt(0)
	v_add_f32_e32 v70, v70, v72
	s_nop 1
	v_mov_b32_dpp v72, v70 quad_perm:[2,3,0,1] row_mask:0xf bank_mask:0xf
	s_waitcnt lgkmcnt(0)
	v_add_f32_e32 v70, v70, v72
	s_nop 1
	v_mov_b32_dpp v72, v70 row_shl:4 row_mask:0xf bank_mask:0x5
	v_mov_b32_dpp v72, v70 row_shr:4 row_mask:0xf bank_mask:0xa
	s_waitcnt lgkmcnt(0)
	v_add_f32_e32 v70, v70, v72
	s_nop 1
	v_mov_b32_dpp v72, v70 row_shl:8 row_mask:0xf bank_mask:0x3
	v_mov_b32_dpp v72, v70 row_shr:8 row_mask:0xf bank_mask:0xc
	s_waitcnt lgkmcnt(0)
	v_add_f32_e32 v70, v70, v72
	v_mov_b32_e32 v72, v70
	v_mov_b32_e32 v238, v70
	s_nop 1
	v_permlane16_swap_b32 v72, v238
	s_waitcnt lgkmcnt(0)
	v_add_f32_e32 v70, v238, v72
	v_mov_b32_e32 v72, v70
	v_mov_b32_e32 v239, v70
	s_nop 1
	v_permlane32_swap_b32 v72, v239
	s_waitcnt lgkmcnt(0)
	v_add_f32_e32 v70, v239, v72
	v_fmac_f32_e32 v83, 0xba800000, v70
	v_fmac_f32_e32 v82, 0xba800000, v70
	v_fmac_f32_e32 v81, 0xba800000, v70
	v_fmac_f32_e32 v80, 0xba800000, v70
	v_fmac_f32_e32 v79, 0xba800000, v70
	v_fmac_f32_e32 v78, 0xba800000, v70
	v_fmac_f32_e32 v77, 0xba800000, v70
	v_fmac_f32_e32 v76, 0xba800000, v70
	v_fmac_f32_e32 v94, 0xba800000, v70
	v_fmac_f32_e32 v97, 0xba800000, v70
	v_fmac_f32_e32 v95, 0xba800000, v70
	v_fmac_f32_e32 v98, 0xba800000, v70
	v_fmac_f32_e32 v71, 0xba800000, v70
	v_fmac_f32_e32 v75, 0xba800000, v70
	v_fmac_f32_e32 v73, 0xba800000, v70
	v_fmac_f32_e32 v96, 0xba800000, v70
	v_mul_f32_e32 v70, v82, v82
	v_mul_f32_e32 v72, v83, v83
	v_mul_f32_e32 v74, v80, v80
	v_mul_f32_e32 v99, v81, v81
	v_mul_f32_e32 v160, v98, v98
	v_mul_f32_e32 v161, v97, v97
	v_fmac_f32_e32 v70, v78, v78
	v_fmac_f32_e32 v72, v79, v79
	v_fmac_f32_e32 v74, v76, v76
	v_fmac_f32_e32 v99, v77, v77
	v_mul_f32_e32 v162, v96, v96
	v_mul_f32_e32 v163, v75, v75
	v_fmac_f32_e32 v160, v95, v95
	v_fmac_f32_e32 v161, v94, v94
	v_add_f32_e32 v70, v70, v72
	v_add_f32_e32 v72, v74, v99
	v_mul_f32_e32 v101, v101, v82
	v_mul_f32_e32 v103, v103, v83
	v_mul_f32_e32 v117, v82, v117
	v_mul_f32_e32 v119, v83, v119
	v_fmac_f32_e32 v162, v73, v73
	v_fmac_f32_e32 v163, v71, v71
	v_add_f32_e32 v74, v160, v161
	v_add_f32_e32 v70, v70, v72
	v_mul_f32_e32 v105, v105, v80
	v_mul_f32_e32 v107, v107, v81
	v_mul_f32_e32 v121, v80, v121
	v_mul_f32_e32 v123, v81, v123
	v_fmac_f32_e32 v101, v100, v78
	v_fmac_f32_e32 v103, v102, v79
	v_fmac_f32_e32 v117, v78, v116
	v_fmac_f32_e32 v119, v79, v118
	v_add_f32_e32 v99, v162, v163
	v_add_f32_e32 v70, v74, v70
	v_mul_f32_e32 v109, v109, v98
	v_mul_f32_e32 v111, v111, v97
	v_mul_f32_e32 v125, v98, v125
	v_mul_f32_e32 v127, v97, v127
	v_fmac_f32_e32 v105, v104, v76
	v_fmac_f32_e32 v107, v106, v77
	v_fmac_f32_e32 v121, v76, v120
	v_fmac_f32_e32 v123, v77, v122
	v_add_f32_e32 v100, v101, v103
	v_add_f32_e32 v70, v99, v70
	v_add_f32_e32 v99, v117, v119
	v_fmac_f32_e32 v109, v108, v95
	v_fmac_f32_e32 v111, v110, v94
	v_fmac_f32_e32 v125, v95, v124
	v_fmac_f32_e32 v127, v94, v126
	v_add_f32_e32 v101, v105, v107
	v_add_f32_e32 v103, v121, v123
	v_add_f32_e32 v100, 0, v100
	v_add_f32_e32 v99, 0, v99
	v_add_f32_e32 v102, v109, v111
	v_add_f32_e32 v104, v125, v127
	v_add_f32_e32 v100, v101, v100
	v_add_f32_e32 v99, v99, v103
	v_add_f32_e32 v100, v102, v100
	v_add_f32_e32 v99, v99, v104
	global_load_dwordx4 v[102:105], v[36:37], off
	global_load_dwordx4 v[106:109], v[38:39], off
	v_mul_f32_e32 v113, v96, v113
	v_mul_f32_e32 v115, v75, v115
	v_fmac_f32_e32 v113, v73, v112
	v_fmac_f32_e32 v115, v71, v114
	v_add_f32_e32 v74, v113, v115
	global_load_dwordx4 v[110:113], v[40:41], off
	global_load_dwordx4 v[114:117], v[42:43], off
	s_waitcnt vmcnt(10)
; __device__ __forceinline__ float wave_sum(float v) {
; #pragma unroll
;     for (int o = 1; o < 64; o <<= 1) v += __shfl_xor(v, o);
;     return v;
; __device__ __forceinline__ void logits_job(const Args& a, const bf16* Z, int lane, int wave) {
;     ...
;         for (int h = 0; h < 8; ++h) { float d = 0.f;
; #pragma unroll
;             for (int j = 0; j < 4; ++j) { const f32x4 w = ((const f32x4*)(WF + h * 1024))[64 * j + lane]; d += (v[j][0] * w[0] + v[j][1] * w[1]) + (v[j][2] * w[2] + v[j][3] * w[3]); }
;             d = wave_sum(d); if (lane == h) mine = d; }
	v_mul_f32_e32 v118, v82, v133
	v_mul_f32_e32 v119, v83, v135
	v_fmac_f32_e32 v118, v78, v132
	v_fmac_f32_e32 v119, v79, v134
	v_add_f32_e32 v118, v118, v119
	v_add_f32_e32 v122, 0, v118
	global_load_dwordx4 v[118:121], v[44:45], off
	v_mul_f32_e32 v129, v96, v129
	v_mul_f32_e32 v101, v75, v131
	v_fmac_f32_e32 v129, v73, v128
	v_fmac_f32_e32 v101, v71, v130
	v_add_f32_e32 v101, v129, v101
	v_add_f32_e32 v74, v74, v100
	v_add_f32_e32 v99, v99, v101
	s_nop 1
	v_mov_b32_dpp v100, v74 quad_perm:[1,0,3,2] row_mask:0xf bank_mask:0xf
	s_nop 1
	v_mov_b32_dpp v101, v99 quad_perm:[1,0,3,2] row_mask:0xf bank_mask:0xf
	s_waitcnt vmcnt(10)
	v_mul_f32_e32 v123, v80, v137
	v_mul_f32_e32 v124, v81, v139
	v_fmac_f32_e32 v123, v76, v136
	s_waitcnt lgkmcnt(0)
	v_add_f32_e32 v74, v74, v100
	s_waitcnt lgkmcnt(0)
	v_add_f32_e32 v99, v99, v101
	s_nop 1
	v_mov_b32_dpp v100, v74 quad_perm:[2,3,0,1] row_mask:0xf bank_mask:0xf
	s_nop 1
	v_mov_b32_dpp v101, v99 quad_perm:[2,3,0,1] row_mask:0xf bank_mask:0xf
	v_fmac_f32_e32 v124, v77, v138
	v_add_f32_e32 v123, v123, v124
	v_add_f32_e32 v122, v122, v123
	s_waitcnt vmcnt(9)
	v_mul_f32_e32 v123, v98, v141
	v_mul_f32_e32 v124, v97, v143
	v_fmac_f32_e32 v123, v95, v140
	v_fmac_f32_e32 v124, v94, v142
	v_add_f32_e32 v123, v123, v124
	s_waitcnt lgkmcnt(0)
	v_add_f32_e32 v74, v74, v100
	s_waitcnt lgkmcnt(0)
	v_add_f32_e32 v99, v99, v101
	v_add_f32_e32 v122, v122, v123
	s_waitcnt vmcnt(8)
	v_mul_f32_e32 v123, v96, v145
	v_mul_f32_e32 v124, v75, v147
	s_nop 1
	v_mov_b32_dpp v100, v74 row_shl:4 row_mask:0xf bank_mask:0x5
	v_mov_b32_dpp v100, v74 row_shr:4 row_mask:0xf bank_mask:0xa
	s_nop 1
	v_mov_b32_dpp v101, v99 row_shl:4 row_mask:0xf bank_mask:0x5
	v_mov_b32_dpp v101, v99 row_shr:4 row_mask:0xf bank_mask:0xa
	v_fmac_f32_e32 v123, v73, v144
	v_fmac_f32_e32 v124, v71, v146
	v_add_f32_e32 v123, v123, v124
	v_add_f32_e32 v122, v122, v123
	s_nop 1
	v_mov_b32_dpp v123, v122 quad_perm:[1,0,3,2] row_mask:0xf bank_mask:0xf
	s_waitcnt lgkmcnt(0)
	v_add_f32_e32 v74, v74, v100
	s_waitcnt lgkmcnt(0)
	v_add_f32_e32 v99, v99, v101
	s_nop 1
	v_mov_b32_dpp v100, v74 row_shl:8 row_mask:0xf bank_mask:0x3
	v_mov_b32_dpp v100, v74 row_shr:8 row_mask:0xf bank_mask:0xc
	s_nop 1
	v_mov_b32_dpp v101, v99 row_shl:8 row_mask:0xf bank_mask:0x3
	v_mov_b32_dpp v101, v99 row_shr:8 row_mask:0xf bank_mask:0xc
	s_waitcnt lgkmcnt(0)
	v_add_f32_e32 v122, v122, v123
	s_nop 1
	v_mov_b32_dpp v123, v122 quad_perm:[2,3,0,1] row_mask:0xf bank_mask:0xf
	s_waitcnt vmcnt(6)
	v_mul_f32_e32 v127, v80, v153
	s_waitcnt lgkmcnt(0)
	v_add_f32_e32 v74, v74, v100
	s_waitcnt lgkmcnt(0)
	v_add_f32_e32 v101, v99, v101
	v_mov_b32_e32 v100, v74
	v_mov_b32_e32 v240, v74
	s_nop 1
	v_permlane16_swap_b32 v100, v240
	v_mov_b32_e32 v124, v101
	v_mov_b32_e32 v241, v101
	s_nop 1
	v_permlane16_swap_b32 v124, v241
	s_waitcnt lgkmcnt(0)
	v_add_f32_e32 v146, v122, v123
	v_mul_f32_e32 v122, v82, v149
	v_mul_f32_e32 v123, v83, v151
	v_fmac_f32_e32 v122, v78, v148
	v_fmac_f32_e32 v123, v79, v150
	v_add_f32_e32 v122, v122, v123
	v_mul_f32_e32 v128, v81, v155
	s_waitcnt lgkmcnt(0)
	v_add_f32_e32 v74, v240, v100
	s_waitcnt lgkmcnt(0)
	v_add_f32_e32 v100, v241, v124
	v_add_f32_e32 v126, 0, v122
	v_fmac_f32_e32 v127, v76, v152
	global_load_dwordx4 v[122:125], v[46:47], off
	v_fmac_f32_e32 v128, v77, v154
	v_add_f32_e32 v127, v127, v128
	v_add_f32_e32 v130, v126, v127
	s_waitcnt vmcnt(6)
	v_mul_f32_e32 v131, v98, v157
	global_load_dwordx4 v[126:129], v[48:49], off
	s_waitcnt vmcnt(6)
	v_mul_f32_e32 v103, v96, v103
	v_fmac_f32_e32 v103, v73, v102
	v_mul_f32_e32 v102, v75, v105
	v_fmac_f32_e32 v102, v71, v104
	s_waitcnt vmcnt(5)
	v_mul_f32_e32 v104, v82, v107
	v_mul_f32_e32 v105, v83, v109
	v_mul_f32_e32 v132, v97, v159
	v_fmac_f32_e32 v104, v78, v106
	v_fmac_f32_e32 v105, v79, v108
	v_fmac_f32_e32 v131, v95, v156
	v_fmac_f32_e32 v132, v94, v158
	v_add_f32_e32 v104, v104, v105
	s_waitcnt vmcnt(4)
	v_mul_f32_e32 v105, v80, v111
	v_mul_f32_e32 v106, v81, v113
	v_add_f32_e32 v131, v131, v132
	v_fmac_f32_e32 v105, v76, v110
	v_fmac_f32_e32 v106, v77, v112
	v_add_f32_e32 v138, v130, v131
	global_load_dwordx4 v[130:133], v[50:51], off
	v_add_f32_e32 v104, 0, v104
	v_add_f32_e32 v105, v105, v106
	v_add_f32_e32 v104, v104, v105
	s_waitcnt vmcnt(4)
	v_mul_f32_e32 v105, v98, v115
	v_mul_f32_e32 v106, v97, v117
	s_nop 1
	v_mov_b32_dpp v147, v146 row_shl:4 row_mask:0xf bank_mask:0x5
	v_mov_b32_dpp v147, v146 row_shr:4 row_mask:0xf bank_mask:0xa
	v_fmac_f32_e32 v105, v95, v114
	v_fmac_f32_e32 v106, v94, v116
	global_load_dwordx4 v[134:137], v[52:53], off
	v_add_f32_e32 v105, v105, v106
	v_add_f32_e32 v102, v103, v102
	v_add_f32_e32 v104, v104, v105
	s_waitcnt vmcnt(4)
	v_mul_f32_e32 v105, v96, v119
	v_add_f32_e32 v102, v138, v102
	global_load_dwordx4 v[138:141], v[54:55], off
	global_load_dwordx4 v[142:145], v[60:61], off
	v_fmac_f32_e32 v105, v73, v118
	v_mul_f32_e32 v106, v75, v121
	global_load_dwordx4 v[116:119], v[62:63], off
	v_fmac_f32_e32 v106, v71, v120
	global_load_dwordx4 v[108:111], v[56:57], off
	global_load_dwordx4 v[112:115], v[58:59], off
	v_add_f32_e32 v105, v105, v106
	s_waitcnt lgkmcnt(0)
	v_add_f32_e32 v106, v146, v147
	global_load_dwordx4 v[146:149], v[64:65], off
	global_load_dwordx4 v[150:153], v[66:67], off
	global_load_dwordx4 v[154:157], v[68:69], off
	s_nop 1
	v_mov_b32_dpp v103, v102 quad_perm:[1,0,3,2] row_mask:0xf bank_mask:0xf
	v_add_f32_e32 v104, v104, v105
	s_nop 1
	v_mov_b32_dpp v105, v104 quad_perm:[1,0,3,2] row_mask:0xf bank_mask:0xf
	s_nop 1
	v_mov_b32_dpp v72, v70 quad_perm:[1,0,3,2] row_mask:0xf bank_mask:0xf
	s_nop 1
	v_mov_b32_dpp v107, v106 row_shl:8 row_mask:0xf bank_mask:0x3
	v_mov_b32_dpp v107, v106 row_shr:8 row_mask:0xf bank_mask:0xc
	s_waitcnt lgkmcnt(0)
; __device__ __forceinline__ float wave_sum(float v) {
; #pragma unroll
;     for (int o = 1; o < 64; o <<= 1) v += __shfl_xor(v, o);
;     return v;
; __device__ __forceinline__ void logits_job(const Args& a, const bf16* Z, int lane, int wave) {
;     ...
;         for (int h = 0; h < 8; ++h) { float d = 0.f;
; #pragma unroll
;             for (int j = 0; j < 4; ++j) { const f32x4 w = ((const f32x4*)(WF + h * 1024))[64 * j + lane]; d += (v[j][0] * w[0] + v[j][1] * w[1]) + (v[j][2] * w[2] + v[j][3] * w[3]); }
;             d = wave_sum(d); if (lane == h) mine = d; }
	v_add_f32_e32 v102, v102, v103
	s_nop 1
	v_mov_b32_dpp v103, v102 quad_perm:[2,3,0,1] row_mask:0xf bank_mask:0xf
	s_waitcnt lgkmcnt(0)
	v_add_f32_e32 v104, v104, v105
	s_nop 1
	v_mov_b32_dpp v105, v104 quad_perm:[2,3,0,1] row_mask:0xf bank_mask:0xf
	s_waitcnt lgkmcnt(0)
	v_add_f32_e32 v70, v70, v72
	s_nop 1
	v_mov_b32_dpp v72, v70 quad_perm:[2,3,0,1] row_mask:0xf bank_mask:0xf
	s_waitcnt lgkmcnt(0)
	v_add_f32_e32 v102, v102, v103
	s_nop 1
	v_mov_b32_dpp v103, v102 row_shl:4 row_mask:0xf bank_mask:0x5
	v_mov_b32_dpp v103, v102 row_shr:4 row_mask:0xf bank_mask:0xa
	s_waitcnt lgkmcnt(0)
	v_add_f32_e32 v104, v104, v105
	s_nop 1
	v_mov_b32_dpp v105, v104 row_shl:4 row_mask:0xf bank_mask:0x5
	v_mov_b32_dpp v105, v104 row_shr:4 row_mask:0xf bank_mask:0xa
	s_waitcnt lgkmcnt(0)
	v_add_f32_e32 v70, v70, v72
	s_nop 1
	v_mov_b32_dpp v72, v70 row_shl:4 row_mask:0xf bank_mask:0x5
	v_mov_b32_dpp v72, v70 row_shr:4 row_mask:0xf bank_mask:0xa
	s_waitcnt lgkmcnt(0)
	v_add_f32_e32 v102, v102, v103
	s_nop 1
	v_mov_b32_dpp v103, v102 row_shl:8 row_mask:0xf bank_mask:0x3
	v_mov_b32_dpp v103, v102 row_shr:8 row_mask:0xf bank_mask:0xc
	s_waitcnt lgkmcnt(0)
	v_add_f32_e32 v104, v104, v105
	s_nop 1
	v_mov_b32_dpp v105, v104 row_shl:8 row_mask:0xf bank_mask:0x3
	v_mov_b32_dpp v105, v104 row_shr:8 row_mask:0xf bank_mask:0xc
	s_waitcnt lgkmcnt(0)
	v_add_f32_e32 v70, v70, v72
	s_nop 1
	v_mov_b32_dpp v72, v70 row_shl:8 row_mask:0xf bank_mask:0x3
	v_mov_b32_dpp v72, v70 row_shr:8 row_mask:0xf bank_mask:0xc
	s_waitcnt lgkmcnt(0)
	v_add_f32_e32 v120, v102, v103
	v_mov_b32_e32 v121, v120
	v_mov_b32_e32 v242, v120
	s_nop 1
	v_permlane16_swap_b32 v121, v242
	s_waitcnt lgkmcnt(0)
	v_add_f32_e32 v158, v104, v105
	v_add_f32_e32 v106, v106, v107
	s_waitcnt lgkmcnt(0)
	v_add_f32_e32 v70, v70, v72
	v_mov_b32_e32 v72, v70
	v_mov_b32_e32 v243, v70
	s_nop 1
	v_permlane16_swap_b32 v72, v243
	s_waitcnt lgkmcnt(0)
	v_add_f32_e32 v104, v242, v121
	s_waitcnt vmcnt(11)
	v_mul_f32_e32 v120, v82, v123
	v_mul_f32_e32 v121, v83, v125
	v_fmac_f32_e32 v120, v78, v122
	v_fmac_f32_e32 v121, v79, v124
	v_add_f32_e32 v120, v120, v121
	s_waitcnt vmcnt(10)
	v_mul_f32_e32 v121, v80, v127
	v_mul_f32_e32 v122, v81, v129
	v_fmac_f32_e32 v121, v76, v126
	v_fmac_f32_e32 v122, v77, v128
	v_add_f32_e32 v120, 0, v120
	v_add_f32_e32 v121, v121, v122
	v_add_f32_e32 v120, v120, v121
	v_mov_b32_e32 v107, v106
	v_mov_b32_e32 v244, v106
	s_nop 1
	v_permlane16_swap_b32 v107, v244
	v_mov_b32_e32 v159, v158
	v_mov_b32_e32 v245, v158
	s_nop 1
	v_permlane16_swap_b32 v159, v245
	s_waitcnt lgkmcnt(0)
	v_add_f32_e32 v70, v243, v72
	ds_bpermute_b32 v72, v90, v70
	ds_bpermute_b32 v99, v90, v74
	s_waitcnt lgkmcnt(0)
	v_add_f32_e32 v102, v244, v107
	s_waitcnt lgkmcnt(0)
	v_add_f32_e32 v106, v245, v159
	ds_bpermute_b32 v101, v90, v100
	ds_bpermute_b32 v103, v90, v102
	ds_bpermute_b32 v105, v90, v104
	s_waitcnt vmcnt(9)
	v_mul_f32_e32 v121, v98, v131
	v_mul_f32_e32 v122, v97, v133
	v_fmac_f32_e32 v121, v95, v130
	v_fmac_f32_e32 v122, v94, v132
	v_add_f32_e32 v121, v121, v122
	v_add_f32_e32 v120, v120, v121
	ds_bpermute_b32 v107, v90, v106
	s_waitcnt vmcnt(8)
	v_mul_f32_e32 v121, v96, v135
	v_mul_f32_e32 v122, v75, v137
	v_fmac_f32_e32 v121, v73, v134
	v_fmac_f32_e32 v122, v71, v136
	v_add_f32_e32 v121, v121, v122
	v_add_f32_e32 v120, v120, v121
	s_waitcnt vmcnt(7)
	v_mul_f32_e32 v122, v82, v139
	v_fmac_f32_e32 v122, v78, v138
	v_mul_f32_e32 v123, v83, v141
	v_fmac_f32_e32 v123, v79, v140
	s_waitcnt vmcnt(5)
	v_mul_f32_e32 v82, v82, v117
	v_fmac_f32_e32 v82, v78, v116
	v_mul_f32_e32 v78, v83, v119
	s_waitcnt vmcnt(4)
	v_mul_f32_e32 v109, v80, v109
	v_fmac_f32_e32 v78, v79, v118
	v_fmac_f32_e32 v109, v76, v108
	s_waitcnt vmcnt(2)
	v_mul_f32_e32 v79, v80, v147
	v_fmac_f32_e32 v79, v76, v146
	v_mul_f32_e32 v76, v81, v149
	v_mul_f32_e32 v108, v81, v111
	v_add_f32_e32 v78, v82, v78
	v_fmac_f32_e32 v76, v77, v148
	v_fmac_f32_e32 v108, v77, v110
	v_add_f32_e32 v78, 0, v78
	v_add_f32_e32 v76, v79, v76
	v_add_f32_e32 v122, v122, v123
	v_add_f32_e32 v108, v109, v108
	v_mul_f32_e32 v109, v98, v113
	v_mul_f32_e32 v110, v97, v115
	v_add_f32_e32 v76, v78, v76
	s_waitcnt vmcnt(1)
	v_mul_f32_e32 v77, v98, v151
	v_mul_f32_e32 v78, v97, v153
	v_add_f32_e32 v122, 0, v122
	v_fmac_f32_e32 v109, v95, v112
	v_fmac_f32_e32 v110, v94, v114
	v_fmac_f32_e32 v77, v95, v150
	v_fmac_f32_e32 v78, v94, v152
	v_add_f32_e32 v108, v122, v108
	v_add_f32_e32 v109, v109, v110
	v_add_f32_e32 v77, v77, v78
	v_add_f32_e32 v108, v108, v109
	v_mul_f32_e32 v109, v96, v143
	v_add_f32_e32 v76, v76, v77
	s_waitcnt vmcnt(0)
	v_mul_f32_e32 v77, v96, v155
	v_fmac_f32_e32 v109, v73, v142
	v_mul_f32_e32 v110, v75, v145
	v_fmac_f32_e32 v77, v73, v154
	v_mul_f32_e32 v73, v75, v157
	v_fmac_f32_e32 v110, v71, v144
	v_fmac_f32_e32 v73, v71, v156
	v_add_f32_e32 v109, v109, v110
	v_add_f32_e32 v71, v77, v73
	v_add_f32_e32 v108, v108, v109
	v_add_f32_e32 v71, v76, v71
	s_nop 1
	v_mov_b32_dpp v121, v120 quad_perm:[1,0,3,2] row_mask:0xf bank_mask:0xf
	s_nop 1
	v_mov_b32_dpp v109, v108 quad_perm:[1,0,3,2] row_mask:0xf bank_mask:0xf
	s_nop 1
	v_mov_b32_dpp v73, v71 quad_perm:[1,0,3,2] row_mask:0xf bank_mask:0xf
	s_waitcnt lgkmcnt(0)
	v_add_f32_e32 v75, v120, v121
	s_waitcnt lgkmcnt(0)
; __device__ __forceinline__ float wave_sum(float v) {
; #pragma unroll
;     for (int o = 1; o < 64; o <<= 1) v += __shfl_xor(v, o);
;     return v;
; __device__ __forceinline__ void logits_job(const Args& a, const bf16* Z, int lane, int wave) {
;     ...
;         for (int h = 0; h < 8; ++h) { float d = 0.f;
; #pragma unroll
;             for (int j = 0; j < 4; ++j) { const f32x4 w = ((const f32x4*)(WF + h * 1024))[64 * j + lane]; d += (v[j][0] * w[0] + v[j][1] * w[1]) + (v[j][2] * w[2] + v[j][3] * w[3]); }
;             d = wave_sum(d); if (lane == h) mine = d; }
;         if (lane < 8) { const float z = mine * rstd + cbf[lane] + bfp[lane];
;             const float e_ = __expf(-fabsf(z)), u_ = 1.f + e_; const float l1p = (u_ == 1.f) ? e_ : __logf(u_) * (e_ / (u_ - 1.f));
;             const float ls = fminf(z, 0.f) - l1p;
;             const int b = m / S, sidx = m % S; LOGF[((size_t)(b * 8 + lane)) * S + sidx] = ls; }
	v_add_f32_e32 v77, v108, v109
	s_waitcnt lgkmcnt(0)
	v_add_f32_e32 v71, v71, v73
	s_nop 1
	v_mov_b32_dpp v76, v75 quad_perm:[2,3,0,1] row_mask:0xf bank_mask:0xf
	s_nop 1
	v_mov_b32_dpp v78, v77 quad_perm:[2,3,0,1] row_mask:0xf bank_mask:0xf
	s_nop 1
	v_mov_b32_dpp v73, v71 quad_perm:[2,3,0,1] row_mask:0xf bank_mask:0xf
	s_waitcnt lgkmcnt(0)
	v_add_f32_e32 v75, v75, v76
	s_waitcnt lgkmcnt(0)
	v_add_f32_e32 v77, v77, v78
	s_waitcnt lgkmcnt(0)
	v_add_f32_e32 v71, v71, v73
	s_nop 1
	v_mov_b32_dpp v76, v75 row_shl:4 row_mask:0xf bank_mask:0x5
	v_mov_b32_dpp v76, v75 row_shr:4 row_mask:0xf bank_mask:0xa
	s_nop 1
	v_mov_b32_dpp v78, v77 row_shl:4 row_mask:0xf bank_mask:0x5
	v_mov_b32_dpp v78, v77 row_shr:4 row_mask:0xf bank_mask:0xa
	s_nop 1
	v_mov_b32_dpp v73, v71 row_shl:4 row_mask:0xf bank_mask:0x5
	v_mov_b32_dpp v73, v71 row_shr:4 row_mask:0xf bank_mask:0xa
	s_waitcnt lgkmcnt(0)
	v_add_f32_e32 v75, v75, v76
	s_waitcnt lgkmcnt(0)
	v_add_f32_e32 v77, v77, v78
	s_waitcnt lgkmcnt(0)
	v_add_f32_e32 v71, v71, v73
	s_nop 1
	v_mov_b32_dpp v76, v75 row_shl:8 row_mask:0xf bank_mask:0x3
	v_mov_b32_dpp v76, v75 row_shr:8 row_mask:0xf bank_mask:0xc
	s_nop 1
	v_mov_b32_dpp v78, v77 row_shl:8 row_mask:0xf bank_mask:0x3
	v_mov_b32_dpp v78, v77 row_shr:8 row_mask:0xf bank_mask:0xc
	s_nop 1
	v_mov_b32_dpp v73, v71 row_shl:8 row_mask:0xf bank_mask:0x3
	v_mov_b32_dpp v73, v71 row_shr:8 row_mask:0xf bank_mask:0xc
	s_waitcnt lgkmcnt(0)
	v_add_f32_e32 v75, v75, v76
	s_waitcnt lgkmcnt(0)
	v_add_f32_e32 v77, v77, v78
	s_waitcnt lgkmcnt(0)
	v_add_f32_e32 v79, v71, v73
	v_mov_b32_e32 v76, v75
	v_mov_b32_e32 v246, v75
	s_nop 1
	v_permlane16_swap_b32 v76, v246
	v_mov_b32_e32 v78, v77
	v_mov_b32_e32 v247, v77
	s_nop 1
	v_permlane16_swap_b32 v78, v247
	v_mov_b32_e32 v80, v79
	v_mov_b32_e32 v248, v79
	s_nop 1
	v_permlane16_swap_b32 v80, v248
	s_waitcnt lgkmcnt(0)
	v_add_f32_e32 v71, v246, v76
	s_waitcnt lgkmcnt(0)
	v_add_f32_e32 v75, v247, v78
	s_waitcnt lgkmcnt(0)
	v_add_f32_e32 v77, v248, v80
	v_mov_b32_e32 v73, v71
	v_mov_b32_e32 v249, v71
	s_nop 1
	v_permlane32_swap_b32 v73, v249
	v_mov_b32_e32 v76, v75
	v_mov_b32_e32 v250, v75
	s_nop 1
	v_permlane32_swap_b32 v76, v250
	v_mov_b32_e32 v78, v77
	v_mov_b32_e32 v251, v77
	s_nop 1
	v_permlane32_swap_b32 v78, v251
	s_and_saveexec_b64 s[12:13], s[38:39]
	s_cbranch_execz .LBB0_416
	global_load_dword v79, v[2:3], off
	global_load_dword v80, v[4:5], off
	v_add_f32_e32 v70, v70, v72
	s_mov_b32 s17, 0xf800000
	v_add_f32_e32 v74, v74, v99
	v_fmamk_f32 v70, v70, 0x3a800000, v91
	s_waitcnt lgkmcnt(0)
	v_add_f32_e32 v72, v251, v78
	v_add_f32_e32 v78, v100, v101
	v_cndmask_b32_e64 v74, 0, v74, s[54:55]
	v_mul_f32_e32 v81, 0x4f800000, v70
	v_cmp_gt_f32_e32 vcc, s17, v70
	v_add_f32_e32 v77, v102, v103
	v_cndmask_b32_e64 v74, v74, v78, s[52:53]
	v_cndmask_b32_e32 v70, v70, v81, vcc
	v_cndmask_b32_e64 v74, v74, v77, s[50:51]
	v_sqrt_f32_e32 v77, v70
	v_add_f32_e32 v75, v250, v76
	v_add_f32_e32 v76, v104, v105
	v_add_f32_e32 v71, v249, v73
	v_add_f32_e32 v73, v106, v107
	v_cndmask_b32_e64 v74, v74, v76, s[48:49]
	v_cndmask_b32_e64 v73, v74, v73, s[46:47]
	v_cndmask_b32_e64 v71, v73, v71, s[44:45]
	v_add_u32_e32 v73, -1, v77
	v_cndmask_b32_e64 v71, v71, v75, s[42:43]
	v_add_u32_e32 v74, 1, v77
	v_fma_f32 v75, -v73, v77, v70
	v_fma_f32 v76, -v74, v77, v70
	v_cmp_ge_f32_e64 s[56:57], 0, v75
	v_cndmask_b32_e64 v71, v71, v72, s[40:41]
	s_mov_b32 s17, 0xbfb8aa3b
	v_cndmask_b32_e64 v73, v77, v73, s[56:57]
	v_cmp_lt_f32_e64 s[56:57], 0, v76
	s_nop 1
	v_cndmask_b32_e64 v73, v73, v74, s[56:57]
	v_mul_f32_e32 v74, 0x37800000, v73
	v_cndmask_b32_e32 v73, v73, v74, vcc
	v_cmp_class_f32_e32 vcc, v70, v92
	s_nop 1
	v_cndmask_b32_e32 v70, v73, v70, vcc
	v_div_scale_f32 v73, s[18:19], v70, v70, 1.0
	v_rcp_f32_e32 v74, v73
	v_div_scale_f32 v72, vcc, 1.0, v70, 1.0
	v_fma_f32 v75, -v73, v74, 1.0
	v_fmac_f32_e32 v74, v75, v74
	v_mul_f32_e32 v75, v72, v74
	v_fma_f32 v76, -v73, v75, v72
	v_fmac_f32_e32 v75, v76, v74
	v_fma_f32 v72, -v73, v75, v72
	v_div_fmas_f32 v72, v72, v74, v75
	v_div_fixup_f32 v70, v72, v70, 1.0
	s_waitcnt vmcnt(1)
	v_fmac_f32_e32 v79, v70, v71
	s_waitcnt vmcnt(0)
	v_add_f32_e32 v70, v79, v80
	v_mul_f32_e64 v71, |v70|, s17
	v_exp_f32_e32 v71, v71
	s_nop 0
	v_add_f32_e32 v72, 1.0, v71
	v_cmp_neq_f32_e32 vcc, 1.0, v72
	s_and_saveexec_b64 s[22:23], vcc
	s_cbranch_execz .LBB0_415
	v_cmp_gt_f32_e32 vcc, s9, v72
	s_nop 1
	v_cndmask_b32_e64 v73, 0, 32, vcc
	v_ldexp_f32 v73, v72, v73
	v_log_f32_e32 v73, v73
	v_add_f32_e32 v72, -1.0, v72
	v_div_scale_f32 v75, s[18:19], v72, v72, v71
	v_mul_f32_e32 v74, 0x3f317217, v73
	v_fma_f32 v74, v73, s15, -v74
	v_rcp_f32_e32 v76, v75
	v_fmac_f32_e32 v74, 0x3377d1cf, v73
	v_fmac_f32_e32 v74, 0x3f317217, v73
	v_cmp_lt_f32_e64 s[56:57], |v73|, s16
	s_nop 1
	v_cndmask_b32_e64 v73, v73, v74, s[56:57]
	v_cndmask_b32_e32 v74, 0, v93, vcc
	v_sub_f32_e32 v73, v73, v74
	v_fma_f32 v74, -v75, v76, 1.0
	v_fmac_f32_e32 v76, v74, v76
	v_div_scale_f32 v74, vcc, v71, v72, v71
	v_mul_f32_e32 v77, v74, v76
	v_fma_f32 v78, -v75, v77, v74
	v_fmac_f32_e32 v77, v78, v76
	v_fma_f32 v74, -v75, v77, v74
	v_div_fmas_f32 v74, v74, v76, v77
	v_div_fixup_f32 v71, v74, v72, v71
	v_mul_f32_e32 v71, v73, v71
	s_branch .LBB0_415
